# MRG-end barrier wait now hosts two w_in_c items per wave (second from the last conversion round); P0 keeps only the remainder
# speedup vs baseline: 1.0974x; 1.0078x over previous
.LBB0_10:
	s_cmp_lg_u32 s98, 0
	s_cbranch_scc1 .Lp0_noskip
	s_cmp_lg_u32 s97, 0x100
	s_cbranch_scc1 .Lp0_noskip
	s_add_i32 s0, s44, 0xffffe000
	s_cmp_lt_u32 s0, 0x1000
	s_cbranch_scc1 .LBB0_9
	s_add_i32 s0, s44, 0xffffd000
	s_cmp_lt_u32 s0, 0x690
	s_cbranch_scc1 .LBB0_9

.LBB0_1001:
	s_or_b64 exec, exec, s[2:3]
	s_waitcnt vmcnt(0)
	s_barrier
	s_cmp_eq_u32 s97, 0x100
	s_cbranch_scc0 .Lb4_skip
	v_readlane_b32 s7, v255, 2
	v_readlane_b32 s6, v255, 7
	s_nop 0
	s_lshr_b32 s7, s7, 6
	s_cmp_eq_u32 s7, 0
	s_cbranch_scc1 .Lb4_skip
	s_cmp_lt_u32 s6, 16
	s_cbranch_scc1 .Lb4_skip
	v_writelane_b32 v186, s14, 0
	v_writelane_b32 v186, s15, 1
	v_writelane_b32 v186, s30, 2
	v_writelane_b32 v186, s34, 3
	v_writelane_b32 v186, s92, 4
	v_writelane_b32 v186, exec_lo, 5
	v_writelane_b32 v186, exec_hi, 6
	s_mov_b64 exec, -1
	v_mov_b32_e32 v167, v1
	v_mov_b32_e32 v168, v5
	v_mov_b32_e32 v169, v21
	v_mov_b32_e32 v170, v24
	v_mov_b32_e32 v171, v25
	v_mov_b32_e32 v172, v26
	v_mov_b32_e32 v173, v27
	v_mov_b32_e32 v174, v30
	v_mov_b32_e32 v175, v31
	v_mov_b32_e32 v176, v34
	v_mov_b32_e32 v177, v35
	v_mov_b32_e32 v178, v47
	v_mov_b32_e32 v179, v48
	v_mov_b32_e32 v180, v49
	v_mov_b32_e32 v181, v73
	v_mov_b32_e32 v182, v86
	v_mov_b32_e32 v183, v87
	v_mov_b32_e32 v184, v104
	v_mov_b32_e32 v185, v105
	s_add_i32 s92, s6, -16
	s_mul_i32 s92, s92, 7
	s_add_i32 s92, s92, s7
	s_add_i32 s92, s92, 0x27ff
	s_mov_b64 s[100:101], s[4:5]
	s_mov_b32 s98, 2
	s_mov_b32 s99, 0x368f
	s_movk_i32 s48, 0x800
	v_readlane_b32 s0, v255, 3
	v_readlane_b32 s1, v255, 4
	v_readlane_b32 s2, v255, 0
	v_readlane_b32 s3, v255, 1
	v_mov_b32_e32 v163, v0
	v_and_b32_e32 v162, 63, v0
	s_lshl_b32 s30, s7, 14
	s_nop 4
	s_branch .Ltr_f2
